# attention output: the eight 8-byte row-per-lane stores paired through v_permlane32_swap into four dwordx4 stores (asm guide 7.3), on top of the K-fragment prefetch version
# baseline (speedup 1.0000x reference)
; __device__ __forceinline__ unsigned cvt_pk_bf16(float lo, float hi) { f32x2_t v = {lo, hi}; bf16x2_t b = __builtin_convertvector(v, bf16x2_t); return __builtin_bit_cast(unsigned, b); }
; __device__ __forceinline__ float bf_lo(unsigned u) { return __uint_as_float(u << 16); }
; __device__ __forceinline__ float bf_hi(unsigned u) { return __uint_as_float(u & 0xffff0000u); }
; __device__ __forceinline__ void attn_phase(LAS unsigned char* lds, const bf16_t* Q, const bf16_t* Kb, const bf16_t* VT, const bf16_t* Zs, bf16_t* OZ, int vcu, int G) {
;     ...
;         bf16_t* op = OZ + (rowbase + q0 + ql) * D + h * 64 + 4 * hi;
; #pragma unroll
;         for (int g4 = 0; g4 < 4; ++g4) {
;             { const u32x2 z2 = zz[g4]; u32x2 wo; wo.x = cvt_pk_bf16(o0[4 * g4] * bf_lo(z2.x), o0[4 * g4 + 1] * bf_hi(z2.x)); wo.y = cvt_pk_bf16(o0[4 * g4 + 2] * bf_lo(z2.y), o0[4 * g4 + 3] * bf_hi(z2.y)); *(u32x2*)(op + 8 * g4) = wo; }
;             { const u32x2 z2 = zz[4 + g4]; u32x2 wo; wo.x = cvt_pk_bf16(o1[4 * g4] * bf_lo(z2.x), o1[4 * g4 + 1] * bf_hi(z2.x)); wo.y = cvt_pk_bf16(o1[4 * g4 + 2] * bf_lo(z2.y), o1[4 * g4 + 3] * bf_hi(z2.y)); *(u32x2*)(op + 32 + 8 * g4) = wo; }
;         }
.LBB0_539:
	v_lshlrev_b64 v[34:35], 10, v[190:191]
	s_waitcnt vmcnt(12)
	v_lshl_add_u64 v[34:35], v[34:35], 1, s[62:63]
	s_mov_b32 s77, s73
	v_lshl_add_u64 v[34:35], v[34:35], 0, s[76:77]
	v_mov_b32_e32 v163, v145
	v_lshl_add_u64 v[34:35], v[34:35], 0, v[162:163]
	v_mul_u32_u24_e32 v238, 56, v1
	v_add_co_u32_e32 v34, vcc, v34, v238
	s_nop 1
	v_addc_co_u32_e32 v35, vcc, 0, v35, vcc
	v_lshlrev_b32_e32 v36, 16, v192
	v_and_b32_e32 v37, 0xffff0000, v192
	v_lshlrev_b32_e32 v38, 16, v193
	v_and_b32_e32 v39, 0xffff0000, v193
	v_pk_mul_f32 v[18:19], v[18:19], v[36:37]
	v_pk_mul_f32 v[20:21], v[20:21], v[38:39]
	v_cvt_pk_bf16_f32 v240, v18, v19
	v_cvt_pk_bf16_f32 v241, v20, v21
	v_lshlrev_b32_e32 v36, 16, v188
	v_and_b32_e32 v37, 0xffff0000, v188
	v_lshlrev_b32_e32 v38, 16, v189
	v_and_b32_e32 v39, 0xffff0000, v189
	v_pk_mul_f32 v[2:3], v[2:3], v[36:37]
	v_pk_mul_f32 v[4:5], v[4:5], v[38:39]
	v_cvt_pk_bf16_f32 v242, v2, v3
	v_cvt_pk_bf16_f32 v243, v4, v5
	s_nop 1
	v_permlane32_swap_b32_e32 v240, v242
	v_permlane32_swap_b32_e32 v241, v243
	s_nop 0
	global_store_dwordx4 v[34:35], v[240:243], off
	v_lshlrev_b32_e32 v36, 16, v186
	v_and_b32_e32 v37, 0xffff0000, v186
	v_lshlrev_b32_e32 v38, 16, v187
	v_and_b32_e32 v39, 0xffff0000, v187
	v_pk_mul_f32 v[22:23], v[22:23], v[36:37]
	v_pk_mul_f32 v[24:25], v[24:25], v[38:39]
	v_cvt_pk_bf16_f32 v244, v22, v23
	v_cvt_pk_bf16_f32 v245, v24, v25
	v_lshlrev_b32_e32 v36, 16, v184
	v_and_b32_e32 v37, 0xffff0000, v184
	v_lshlrev_b32_e32 v38, 16, v185
	v_and_b32_e32 v39, 0xffff0000, v185
	v_pk_mul_f32 v[6:7], v[6:7], v[36:37]
	v_pk_mul_f32 v[8:9], v[8:9], v[38:39]
	v_cvt_pk_bf16_f32 v246, v6, v7
	v_cvt_pk_bf16_f32 v247, v8, v9
	s_nop 1
	v_permlane32_swap_b32_e32 v244, v246
	v_permlane32_swap_b32_e32 v245, v247
	s_nop 0
	global_store_dwordx4 v[34:35], v[244:247], off offset:16
	v_lshlrev_b32_e32 v36, 16, v182
	v_and_b32_e32 v37, 0xffff0000, v182
	v_lshlrev_b32_e32 v38, 16, v183
	v_and_b32_e32 v39, 0xffff0000, v183
	v_pk_mul_f32 v[26:27], v[26:27], v[36:37]
	v_pk_mul_f32 v[28:29], v[28:29], v[38:39]
	v_cvt_pk_bf16_f32 v248, v26, v27
	v_cvt_pk_bf16_f32 v249, v28, v29
	v_lshlrev_b32_e32 v36, 16, v180
	v_and_b32_e32 v37, 0xffff0000, v180
	v_lshlrev_b32_e32 v38, 16, v181
	v_and_b32_e32 v39, 0xffff0000, v181
	v_pk_mul_f32 v[10:11], v[10:11], v[36:37]
	v_pk_mul_f32 v[12:13], v[12:13], v[38:39]
	v_cvt_pk_bf16_f32 v250, v10, v11
	v_cvt_pk_bf16_f32 v251, v12, v13
	s_nop 1
	v_permlane32_swap_b32_e32 v248, v250
	v_permlane32_swap_b32_e32 v249, v251
	s_nop 0
	global_store_dwordx4 v[34:35], v[248:251], off offset:32
	v_lshlrev_b32_e32 v36, 16, v178
	v_and_b32_e32 v37, 0xffff0000, v178
	v_lshlrev_b32_e32 v38, 16, v179
	v_and_b32_e32 v39, 0xffff0000, v179
	v_pk_mul_f32 v[30:31], v[30:31], v[36:37]
	v_pk_mul_f32 v[32:33], v[32:33], v[38:39]
	v_cvt_pk_bf16_f32 v252, v30, v31
	v_cvt_pk_bf16_f32 v253, v32, v33
	v_lshlrev_b32_e32 v36, 16, v176
	v_and_b32_e32 v37, 0xffff0000, v176
	v_lshlrev_b32_e32 v38, 16, v177
	v_and_b32_e32 v39, 0xffff0000, v177
	v_pk_mul_f32 v[14:15], v[14:15], v[36:37]
	v_pk_mul_f32 v[16:17], v[16:17], v[38:39]
	v_cvt_pk_bf16_f32 v254, v14, v15
	v_cvt_pk_bf16_f32 v255, v16, v17
	s_nop 1
	v_permlane32_swap_b32_e32 v252, v254
	v_permlane32_swap_b32_e32 v253, v255
	s_nop 0
	global_store_dwordx4 v[34:35], v[252:255], off offset:48
	s_andn2_b64 vcc, exec, s[74:75]
	s_add_i32 s89, s89, s3
	s_barrier
	s_cbranch_vccz .LBB0_557
